# G5 epilogue HID stores made nontemporal (on top of G6 pipelined epilogue)
# baseline (speedup 1.0000x reference)
; DI unsigned pk2(float lo, float hi) { return pg8::cvt_pk_bf16(lo, hi); }
;     DI void operator()(const f32x4 (&acc)[2][2][4][2], const Unit& u, int wr, int wc, int fr, int fq) const {
;         const int row0 = u.pm * 256 + wr * 64 + fr, col0 = u.pn * 256 + wc * 32 + 8 * fq;
;         const int bb = (grow0 + u.pm * 256) >> 11;
;         f32x4 bs[2][2];
; #pragma unroll
;         for (int bj = 0; bj < 2; ++bj) { const float* bp = bias2 + (size_t)bb * 4096 + col0 + bj * 128; bs[bj][0] = *(const f32x4*)bp; bs[bj][1] = *(const f32x4*)(bp + 4); }
; #pragma unroll
;         for (int ai = 0; ai < 2; ++ai)
; #pragma unroll
;             for (int m = 0; m < 4; ++m) { bf16* rowp = O + (size_t)(row0 + ai * 128 + m * 16) * 4096 + col0;
;                 const float rstd = rsqrtf(rowss[row0 + ai * 128 + m * 16] * (1.0f / 1024.0f) + 1e-6f);
; #pragma unroll
;                 for (int bj = 0; bj < 2; ++bj) { f32x4 v0 = acc[ai][bj][m][0] * rstd + bs[bj][0], v1 = acc[ai][bj][m][1] * rstd + bs[bj][1];
; #pragma unroll
;                     for (int i = 0; i < 4; ++i) { float a = fmaxf(v0[i], 0.f), b = fmaxf(v1[i], 0.f); v0[i] = a * a; v1[i] = b * b; }
;                     v4u w; w.x = pk2(v0[0], v0[1]); w.y = pk2(v0[2], v0[3]); w.z = pk2(v1[0], v1[1]); w.w = pk2(v1[2], v1[3]);
;                     *(v4u*)(rowp + bj * 128) = w; } }
.LBB0_742:
	s_lshl_b32 s17, s38, 8
	v_readlane_b32 s2, v254, 56
	s_add_i32 s2, s17, s2
	v_readlane_b32 s3, v254, 57
	s_ashr_i32 s2, s2, 11
	s_ashr_i32 s3, s2, 31
	v_add_u32_e32 v160, s17, v180
	v_lshl_or_b32 v156, s37, 8, v182
	s_lshl_b64 s[2:3], s[2:3], 14
	v_readlane_b32 s24, v251, 44
	v_ashrrev_i32_e32 v161, 31, v160
	v_readlane_b32 s25, v251, 45
	s_add_u32 s2, s24, s2
	v_ashrrev_i32_e32 v157, 31, v156
	v_lshlrev_b64 v[158:159], 13, v[160:161]
	s_addc_u32 s3, s25, s3
	v_lshl_add_u64 v[158:159], s[86:87], 0, v[158:159]
	v_lshlrev_b64 v[178:179], 1, v[156:157]
	v_lshl_add_u64 v[46:47], v[156:157], 2, s[2:3]
	v_lshl_add_u64 v[156:157], v[158:159], 0, v[178:179]
	v_lshl_add_u64 v[158:159], v[160:161], 2, s[12:13]
	global_load_dwordx4 v[58:61], v[46:47], off offset:16
	global_load_dwordx4 v[62:65], v[46:47], off
	global_load_dwordx4 v[42:45], v[46:47], off offset:528
	s_nop 0
	global_load_dwordx4 v[46:49], v[46:47], off offset:512
	s_mov_b32 s17, 0x800000
	global_load_dword v161, v[158:159], off
	s_mov_b64 s[2:3], 0x100000
	s_waitcnt vmcnt(0)
	v_fmamk_f32 v161, v161, 0x3a800000, v192
	v_cmp_gt_f32_e32 vcc, s17, v161
	v_mul_f32_e32 v162, 0x4b800000, v161
	s_nop 0
	v_cndmask_b32_e32 v161, v161, v162, vcc
	v_rsq_f32_e32 v161, v161
	s_nop 0
	v_mul_f32_e32 v162, 0x45800000, v161
	v_cndmask_b32_e32 v162, v161, v162, vcc
	v_pk_fma_f32 v[138:139], v[138:139], v[162:163], v[58:59] op_sel_hi:[1,0,1]
	v_pk_fma_f32 v[142:143], v[142:143], v[162:163], v[62:63] op_sel_hi:[1,0,1]
	v_pk_fma_f32 v[140:141], v[140:141], v[162:163], v[60:61] op_sel_hi:[1,0,1]
	v_max_f32_e32 v138, 0, v138
	v_pk_fma_f32 v[144:145], v[144:145], v[162:163], v[64:65] op_sel_hi:[1,0,1]
	v_mul_f32_e32 v161, v138, v138
	v_max_f32_e32 v138, 0, v143
	v_max_f32_e32 v139, 0, v139
	v_max_f32_e32 v140, 0, v140
	v_max_f32_e32 v142, 0, v142
	v_mul_f32_e32 v138, v138, v138
	v_mul_f32_e32 v143, v139, v139
	v_max_f32_e32 v139, 0, v144
	v_mul_f32_e32 v144, v140, v140
	v_max_f32_e32 v140, 0, v145
	v_max_f32_e32 v141, 0, v141
	v_pk_fma_f32 v[132:133], v[132:133], v[162:163], v[44:45] op_sel_hi:[1,0,1]
	v_pk_fma_f32 v[130:131], v[130:131], v[162:163], v[42:43] op_sel_hi:[1,0,1]
	v_mul_f32_e32 v142, v142, v142
	v_mul_f32_e32 v139, v139, v139
	v_mul_f32_e32 v140, v140, v140
	v_mul_f32_e32 v141, v141, v141
	v_cvt_pk_bf16_f32 v138, v142, v138
	v_pk_fma_f32 v[136:137], v[136:137], v[162:163], v[48:49] op_sel_hi:[1,0,1]
	v_pk_fma_f32 v[134:135], v[134:135], v[162:163], v[46:47] op_sel_hi:[1,0,1]
	v_max_f32_e32 v130, 0, v130
	v_max_f32_e32 v131, 0, v131
	v_max_f32_e32 v132, 0, v132
	v_cvt_pk_bf16_f32 v139, v139, v140
	v_cvt_pk_bf16_f32 v140, v161, v143
	v_cvt_pk_bf16_f32 v141, v144, v141
	global_store_dwordx4 v[156:157], v[138:141], off nt
	v_max_f32_e32 v133, 0, v133
	v_max_f32_e32 v134, 0, v134
	v_mul_f32_e32 v138, v130, v130
	v_max_f32_e32 v130, 0, v135
	v_mul_f32_e32 v135, v131, v131
	v_max_f32_e32 v131, 0, v136
	v_mul_f32_e32 v136, v132, v132
	v_max_f32_e32 v132, 0, v137
	v_mul_f32_e32 v130, v130, v130
	v_mul_f32_e32 v131, v131, v131
	v_mul_f32_e32 v132, v132, v132
	v_mul_f32_e32 v133, v133, v133
	v_mul_f32_e32 v134, v134, v134
	v_cvt_pk_bf16_f32 v130, v134, v130
	v_cvt_pk_bf16_f32 v131, v131, v132
	v_cvt_pk_bf16_f32 v132, v138, v135
	v_cvt_pk_bf16_f32 v133, v136, v133
	global_store_dwordx4 v[156:157], v[130:133], off offset:256 nt
	global_load_dword v132, v[158:159], off offset:64
	s_nop 0
	v_or_b32_e32 v130, 16, v160
	v_ashrrev_i32_e32 v131, 31, v130
	v_lshlrev_b64 v[130:131], 13, v[130:131]
	v_lshl_add_u64 v[130:131], s[86:87], 0, v[130:131]
	v_lshl_add_u64 v[130:131], v[130:131], 0, v[178:179]
	s_waitcnt vmcnt(0)
	v_fmamk_f32 v132, v132, 0x3a800000, v192
	v_cmp_gt_f32_e32 vcc, s17, v132
	v_mul_f32_e32 v133, 0x4b800000, v132
	s_nop 0
	v_cndmask_b32_e32 v132, v132, v133, vcc
	v_rsq_f32_e32 v132, v132
	s_nop 0
	v_mul_f32_e32 v133, 0x45800000, v132
	v_cndmask_b32_e32 v132, v132, v133, vcc
	v_pk_fma_f32 v[122:123], v[122:123], v[132:133], v[58:59] op_sel_hi:[1,0,1]
	v_pk_fma_f32 v[126:127], v[126:127], v[132:133], v[62:63] op_sel_hi:[1,0,1]
	v_pk_fma_f32 v[124:125], v[124:125], v[132:133], v[60:61] op_sel_hi:[1,0,1]
	v_max_f32_e32 v122, 0, v122
	v_pk_fma_f32 v[128:129], v[128:129], v[132:133], v[64:65] op_sel_hi:[1,0,1]
	v_mul_f32_e32 v133, v122, v122
	v_max_f32_e32 v122, 0, v127
	v_max_f32_e32 v123, 0, v123
	v_max_f32_e32 v124, 0, v124
	v_max_f32_e32 v126, 0, v126
	v_mul_f32_e32 v122, v122, v122
	v_mul_f32_e32 v127, v123, v123
	v_max_f32_e32 v123, 0, v128
	v_mul_f32_e32 v128, v124, v124
	v_max_f32_e32 v124, 0, v129
	v_max_f32_e32 v125, 0, v125
	v_pk_fma_f32 v[116:117], v[116:117], v[132:133], v[44:45] op_sel_hi:[1,0,1]
	v_pk_fma_f32 v[114:115], v[114:115], v[132:133], v[42:43] op_sel_hi:[1,0,1]
	v_mul_f32_e32 v126, v126, v126
	v_mul_f32_e32 v123, v123, v123
	v_mul_f32_e32 v124, v124, v124
	v_mul_f32_e32 v125, v125, v125
	v_cvt_pk_bf16_f32 v122, v126, v122
	v_pk_fma_f32 v[120:121], v[120:121], v[132:133], v[48:49] op_sel_hi:[1,0,1]
	v_pk_fma_f32 v[118:119], v[118:119], v[132:133], v[46:47] op_sel_hi:[1,0,1]
	v_max_f32_e32 v114, 0, v114
	v_max_f32_e32 v115, 0, v115
	v_max_f32_e32 v116, 0, v116
	v_cvt_pk_bf16_f32 v123, v123, v124
	v_cvt_pk_bf16_f32 v124, v133, v127
	v_cvt_pk_bf16_f32 v125, v128, v125
	global_store_dwordx4 v[130:131], v[122:125], off nt
	v_max_f32_e32 v117, 0, v117
	v_max_f32_e32 v118, 0, v118
	v_mul_f32_e32 v122, v114, v114
	v_max_f32_e32 v114, 0, v119
	v_mul_f32_e32 v119, v115, v115
	v_max_f32_e32 v115, 0, v120
	v_mul_f32_e32 v120, v116, v116
	v_max_f32_e32 v116, 0, v121
	v_mul_f32_e32 v114, v114, v114
	v_mul_f32_e32 v115, v115, v115
	v_mul_f32_e32 v116, v116, v116
	v_mul_f32_e32 v117, v117, v117
	v_mul_f32_e32 v118, v118, v118
	v_cvt_pk_bf16_f32 v114, v118, v114
	v_cvt_pk_bf16_f32 v115, v115, v116
	v_cvt_pk_bf16_f32 v116, v122, v119
	v_cvt_pk_bf16_f32 v117, v120, v117
	global_store_dwordx4 v[130:131], v[114:117], off offset:256 nt
	global_load_dword v116, v[158:159], off offset:128
	s_nop 0
	v_or_b32_e32 v114, 32, v160
	v_ashrrev_i32_e32 v115, 31, v114
	v_lshlrev_b64 v[114:115], 13, v[114:115]
	v_lshl_add_u64 v[114:115], s[86:87], 0, v[114:115]
	v_lshl_add_u64 v[114:115], v[114:115], 0, v[178:179]
	s_waitcnt vmcnt(0)
; DI unsigned pk2(float lo, float hi) { return pg8::cvt_pk_bf16(lo, hi); }
;     DI void operator()(const f32x4 (&acc)[2][2][4][2], const Unit& u, int wr, int wc, int fr, int fq) const {
;     ...
;         for (int ai = 0; ai < 2; ++ai)
; #pragma unroll
;             for (int m = 0; m < 4; ++m) { bf16* rowp = O + (size_t)(row0 + ai * 128 + m * 16) * 4096 + col0;
;                 const float rstd = rsqrtf(rowss[row0 + ai * 128 + m * 16] * (1.0f / 1024.0f) + 1e-6f);
; #pragma unroll
;                 for (int bj = 0; bj < 2; ++bj) { f32x4 v0 = acc[ai][bj][m][0] * rstd + bs[bj][0], v1 = acc[ai][bj][m][1] * rstd + bs[bj][1];
; #pragma unroll
;                     for (int i = 0; i < 4; ++i) { float a = fmaxf(v0[i], 0.f), b = fmaxf(v1[i], 0.f); v0[i] = a * a; v1[i] = b * b; }
;                     v4u w; w.x = pk2(v0[0], v0[1]); w.y = pk2(v0[2], v0[3]); w.z = pk2(v1[0], v1[1]); w.w = pk2(v1[2], v1[3]);
;                     *(v4u*)(rowp + bj * 128) = w; } }
	v_fmamk_f32 v116, v116, 0x3a800000, v192
	v_cmp_gt_f32_e32 vcc, s17, v116
	v_mul_f32_e32 v117, 0x4b800000, v116
	s_nop 0
	v_cndmask_b32_e32 v116, v116, v117, vcc
	v_rsq_f32_e32 v116, v116
	s_nop 0
	v_mul_f32_e32 v117, 0x45800000, v116
	v_cndmask_b32_e32 v116, v116, v117, vcc
	v_pk_fma_f32 v[106:107], v[106:107], v[116:117], v[58:59] op_sel_hi:[1,0,1]
	v_pk_fma_f32 v[110:111], v[110:111], v[116:117], v[62:63] op_sel_hi:[1,0,1]
	v_pk_fma_f32 v[108:109], v[108:109], v[116:117], v[60:61] op_sel_hi:[1,0,1]
	v_max_f32_e32 v106, 0, v106
	v_pk_fma_f32 v[112:113], v[112:113], v[116:117], v[64:65] op_sel_hi:[1,0,1]
	v_mul_f32_e32 v117, v106, v106
	v_max_f32_e32 v106, 0, v111
	v_max_f32_e32 v107, 0, v107
	v_max_f32_e32 v108, 0, v108
	v_max_f32_e32 v110, 0, v110
	v_mul_f32_e32 v106, v106, v106
	v_mul_f32_e32 v111, v107, v107
	v_max_f32_e32 v107, 0, v112
	v_mul_f32_e32 v112, v108, v108
	v_max_f32_e32 v108, 0, v113
	v_max_f32_e32 v109, 0, v109
	v_pk_fma_f32 v[100:101], v[100:101], v[116:117], v[44:45] op_sel_hi:[1,0,1]
	v_pk_fma_f32 v[98:99], v[98:99], v[116:117], v[42:43] op_sel_hi:[1,0,1]
	v_mul_f32_e32 v110, v110, v110
	v_mul_f32_e32 v107, v107, v107
	v_mul_f32_e32 v108, v108, v108
	v_mul_f32_e32 v109, v109, v109
	v_cvt_pk_bf16_f32 v106, v110, v106
	v_pk_fma_f32 v[104:105], v[104:105], v[116:117], v[48:49] op_sel_hi:[1,0,1]
	v_pk_fma_f32 v[102:103], v[102:103], v[116:117], v[46:47] op_sel_hi:[1,0,1]
	v_max_f32_e32 v98, 0, v98
	v_max_f32_e32 v99, 0, v99
	v_max_f32_e32 v100, 0, v100
	v_cvt_pk_bf16_f32 v107, v107, v108
	v_cvt_pk_bf16_f32 v108, v117, v111
	v_cvt_pk_bf16_f32 v109, v112, v109
	global_store_dwordx4 v[114:115], v[106:109], off nt
	v_max_f32_e32 v101, 0, v101
	v_max_f32_e32 v102, 0, v102
	v_mul_f32_e32 v106, v98, v98
	v_max_f32_e32 v98, 0, v103
	v_mul_f32_e32 v103, v99, v99
	v_max_f32_e32 v99, 0, v104
	v_mul_f32_e32 v104, v100, v100
	v_max_f32_e32 v100, 0, v105
	v_mul_f32_e32 v98, v98, v98
	v_mul_f32_e32 v99, v99, v99
	v_mul_f32_e32 v100, v100, v100
	v_mul_f32_e32 v101, v101, v101
	v_mul_f32_e32 v102, v102, v102
	v_cvt_pk_bf16_f32 v98, v102, v98
	v_cvt_pk_bf16_f32 v99, v99, v100
	v_cvt_pk_bf16_f32 v100, v106, v103
	v_cvt_pk_bf16_f32 v101, v104, v101
	global_store_dwordx4 v[114:115], v[98:101], off offset:256 nt
	global_load_dword v100, v[158:159], off offset:192
	s_nop 0
	v_or_b32_e32 v98, 48, v160
	v_ashrrev_i32_e32 v99, 31, v98
	v_lshlrev_b64 v[98:99], 13, v[98:99]
	v_lshl_add_u64 v[98:99], s[86:87], 0, v[98:99]
	v_lshl_add_u64 v[98:99], v[98:99], 0, v[178:179]
	s_waitcnt vmcnt(0)
	v_fmamk_f32 v100, v100, 0x3a800000, v192
	v_cmp_gt_f32_e32 vcc, s17, v100
	v_mul_f32_e32 v101, 0x4b800000, v100
	s_nop 0
	v_cndmask_b32_e32 v100, v100, v101, vcc
	v_rsq_f32_e32 v100, v100
	s_nop 0
	v_mul_f32_e32 v101, 0x45800000, v100
	v_cndmask_b32_e32 v100, v100, v101, vcc
	v_pk_fma_f32 v[90:91], v[90:91], v[100:101], v[58:59] op_sel_hi:[1,0,1]
	v_pk_fma_f32 v[94:95], v[94:95], v[100:101], v[62:63] op_sel_hi:[1,0,1]
	v_pk_fma_f32 v[92:93], v[92:93], v[100:101], v[60:61] op_sel_hi:[1,0,1]
	v_max_f32_e32 v90, 0, v90
	v_pk_fma_f32 v[96:97], v[96:97], v[100:101], v[64:65] op_sel_hi:[1,0,1]
	v_mul_f32_e32 v101, v90, v90
	v_max_f32_e32 v90, 0, v95
	v_max_f32_e32 v91, 0, v91
	v_max_f32_e32 v92, 0, v92
	v_max_f32_e32 v94, 0, v94
	v_mul_f32_e32 v90, v90, v90
	v_mul_f32_e32 v95, v91, v91
	v_max_f32_e32 v91, 0, v96
	v_mul_f32_e32 v96, v92, v92
	v_max_f32_e32 v92, 0, v97
	v_max_f32_e32 v93, 0, v93
	v_pk_fma_f32 v[84:85], v[84:85], v[100:101], v[44:45] op_sel_hi:[1,0,1]
	v_pk_fma_f32 v[82:83], v[82:83], v[100:101], v[42:43] op_sel_hi:[1,0,1]
	v_mul_f32_e32 v94, v94, v94
	v_mul_f32_e32 v91, v91, v91
	v_mul_f32_e32 v92, v92, v92
	v_mul_f32_e32 v93, v93, v93
	v_cvt_pk_bf16_f32 v90, v94, v90
	v_pk_fma_f32 v[88:89], v[88:89], v[100:101], v[48:49] op_sel_hi:[1,0,1]
	v_pk_fma_f32 v[86:87], v[86:87], v[100:101], v[46:47] op_sel_hi:[1,0,1]
	v_max_f32_e32 v82, 0, v82
	v_max_f32_e32 v83, 0, v83
	v_max_f32_e32 v84, 0, v84
	v_cvt_pk_bf16_f32 v91, v91, v92
	v_cvt_pk_bf16_f32 v92, v101, v95
	v_cvt_pk_bf16_f32 v93, v96, v93
	global_store_dwordx4 v[98:99], v[90:93], off nt
	v_max_f32_e32 v85, 0, v85
	v_max_f32_e32 v86, 0, v86
	v_mul_f32_e32 v90, v82, v82
	v_max_f32_e32 v82, 0, v87
	v_mul_f32_e32 v87, v83, v83
	v_max_f32_e32 v83, 0, v88
	v_mul_f32_e32 v88, v84, v84
	v_max_f32_e32 v84, 0, v89
	v_mul_f32_e32 v82, v82, v82
	v_mul_f32_e32 v83, v83, v83
	v_mul_f32_e32 v84, v84, v84
	v_mul_f32_e32 v85, v85, v85
	v_mul_f32_e32 v86, v86, v86
	v_cvt_pk_bf16_f32 v82, v86, v82
	v_cvt_pk_bf16_f32 v83, v83, v84
	v_cvt_pk_bf16_f32 v84, v90, v87
	v_cvt_pk_bf16_f32 v85, v88, v85
	global_store_dwordx4 v[98:99], v[82:85], off offset:256 nt
	global_load_dword v84, v[158:159], off offset:512
	s_nop 0
	v_lshl_add_u64 v[82:83], v[156:157], 0, s[2:3]
	s_mov_b32 s2, 0x100000
	s_waitcnt vmcnt(0)
; DI unsigned pk2(float lo, float hi) { return pg8::cvt_pk_bf16(lo, hi); }
;     DI void operator()(const f32x4 (&acc)[2][2][4][2], const Unit& u, int wr, int wc, int fr, int fq) const {
;     ...
;         for (int ai = 0; ai < 2; ++ai)
; #pragma unroll
;             for (int m = 0; m < 4; ++m) { bf16* rowp = O + (size_t)(row0 + ai * 128 + m * 16) * 4096 + col0;
;                 const float rstd = rsqrtf(rowss[row0 + ai * 128 + m * 16] * (1.0f / 1024.0f) + 1e-6f);
; #pragma unroll
;                 for (int bj = 0; bj < 2; ++bj) { f32x4 v0 = acc[ai][bj][m][0] * rstd + bs[bj][0], v1 = acc[ai][bj][m][1] * rstd + bs[bj][1];
; #pragma unroll
;                     for (int i = 0; i < 4; ++i) { float a = fmaxf(v0[i], 0.f), b = fmaxf(v1[i], 0.f); v0[i] = a * a; v1[i] = b * b; }
;                     v4u w; w.x = pk2(v0[0], v0[1]); w.y = pk2(v0[2], v0[3]); w.z = pk2(v1[0], v1[1]); w.w = pk2(v1[2], v1[3]);
;                     *(v4u*)(rowp + bj * 128) = w; } }
	v_fmamk_f32 v84, v84, 0x3a800000, v192
	v_cmp_gt_f32_e32 vcc, s17, v84
	v_mul_f32_e32 v85, 0x4b800000, v84
	s_nop 0
	v_cndmask_b32_e32 v84, v84, v85, vcc
	v_rsq_f32_e32 v84, v84
	s_nop 0
	v_mul_f32_e32 v85, 0x45800000, v84
	v_cndmask_b32_e32 v84, v84, v85, vcc
	v_pk_fma_f32 v[74:75], v[74:75], v[84:85], v[58:59] op_sel_hi:[1,0,1]
	v_pk_fma_f32 v[78:79], v[78:79], v[84:85], v[62:63] op_sel_hi:[1,0,1]
	v_pk_fma_f32 v[76:77], v[76:77], v[84:85], v[60:61] op_sel_hi:[1,0,1]
	v_max_f32_e32 v74, 0, v74
	v_pk_fma_f32 v[80:81], v[80:81], v[84:85], v[64:65] op_sel_hi:[1,0,1]
	v_max_f32_e32 v78, 0, v78
	v_mul_f32_e32 v85, v74, v74
	v_max_f32_e32 v74, 0, v79
	v_max_f32_e32 v75, 0, v75
	v_max_f32_e32 v76, 0, v76
	v_mul_f32_e32 v78, v78, v78
	v_mul_f32_e32 v74, v74, v74
	v_mul_f32_e32 v79, v75, v75
	v_max_f32_e32 v75, 0, v80
	v_mul_f32_e32 v80, v76, v76
	v_max_f32_e32 v76, 0, v81
	v_mul_f32_e32 v75, v75, v75
	v_max_f32_e32 v77, 0, v77
	v_mul_f32_e32 v76, v76, v76
	v_cvt_pk_bf16_f32 v74, v78, v74
	v_add_co_u32_e32 v78, vcc, s2, v156
	v_pk_fma_f32 v[68:69], v[68:69], v[84:85], v[44:45] op_sel_hi:[1,0,1]
	v_pk_fma_f32 v[66:67], v[66:67], v[84:85], v[42:43] op_sel_hi:[1,0,1]
	v_mul_f32_e32 v77, v77, v77
	v_cvt_pk_bf16_f32 v75, v75, v76
	v_cvt_pk_bf16_f32 v76, v85, v79
	v_addc_co_u32_e32 v79, vcc, 0, v157, vcc
	v_pk_fma_f32 v[72:73], v[72:73], v[84:85], v[48:49] op_sel_hi:[1,0,1]
	v_pk_fma_f32 v[70:71], v[70:71], v[84:85], v[46:47] op_sel_hi:[1,0,1]
	v_max_f32_e32 v66, 0, v66
	v_max_f32_e32 v67, 0, v67
	v_max_f32_e32 v68, 0, v68
	v_cvt_pk_bf16_f32 v77, v80, v77
	global_store_dwordx4 v[78:79], v[74:77], off nt
	v_max_f32_e32 v69, 0, v69
	v_max_f32_e32 v70, 0, v70
	v_mul_f32_e32 v74, v66, v66
	v_max_f32_e32 v66, 0, v71
	v_mul_f32_e32 v71, v67, v67
	v_max_f32_e32 v67, 0, v72
	v_mul_f32_e32 v72, v68, v68
	v_max_f32_e32 v68, 0, v73
	v_mul_f32_e32 v66, v66, v66
	v_mul_f32_e32 v67, v67, v67
	v_mul_f32_e32 v68, v68, v68
	v_mul_f32_e32 v69, v69, v69
	v_mul_f32_e32 v70, v70, v70
	v_cvt_pk_bf16_f32 v66, v70, v66
	v_cvt_pk_bf16_f32 v67, v67, v68
	v_cvt_pk_bf16_f32 v68, v74, v71
	v_cvt_pk_bf16_f32 v69, v72, v69
	global_store_dwordx4 v[82:83], v[66:69], off offset:256 nt
	global_load_dword v68, v[158:159], off offset:576
	s_mov_b64 s[2:3], 0x120000
	v_lshl_add_u64 v[66:67], v[156:157], 0, s[2:3]
	s_mov_b32 s2, 0x120000
	s_waitcnt vmcnt(0)
	v_fmamk_f32 v68, v68, 0x3a800000, v192
	v_cmp_gt_f32_e32 vcc, s17, v68
	v_mul_f32_e32 v69, 0x4b800000, v68
	s_nop 0
	v_cndmask_b32_e32 v68, v68, v69, vcc
	v_rsq_f32_e32 v68, v68
	s_nop 0
	v_mul_f32_e32 v69, 0x45800000, v68
	v_cndmask_b32_e32 v68, v68, v69, vcc
	v_pk_fma_f32 v[50:51], v[50:51], v[68:69], v[58:59] op_sel_hi:[1,0,1]
	v_pk_fma_f32 v[54:55], v[54:55], v[68:69], v[62:63] op_sel_hi:[1,0,1]
	v_pk_fma_f32 v[52:53], v[52:53], v[68:69], v[60:61] op_sel_hi:[1,0,1]
	v_max_f32_e32 v50, 0, v50
	v_pk_fma_f32 v[56:57], v[56:57], v[68:69], v[64:65] op_sel_hi:[1,0,1]
	v_max_f32_e32 v54, 0, v54
	v_mul_f32_e32 v69, v50, v50
	v_max_f32_e32 v50, 0, v55
	v_max_f32_e32 v51, 0, v51
	v_max_f32_e32 v52, 0, v52
	v_mul_f32_e32 v54, v54, v54
	v_mul_f32_e32 v50, v50, v50
	v_mul_f32_e32 v55, v51, v51
	v_max_f32_e32 v51, 0, v56
	v_mul_f32_e32 v56, v52, v52
	v_max_f32_e32 v52, 0, v57
	v_mul_f32_e32 v51, v51, v51
	v_max_f32_e32 v53, 0, v53
	v_mul_f32_e32 v52, v52, v52
	v_cvt_pk_bf16_f32 v50, v54, v50
	v_add_co_u32_e32 v54, vcc, s2, v156
	v_pk_fma_f32 v[36:37], v[36:37], v[68:69], v[44:45] op_sel_hi:[1,0,1]
	v_pk_fma_f32 v[34:35], v[34:35], v[68:69], v[42:43] op_sel_hi:[1,0,1]
	v_mul_f32_e32 v53, v53, v53
	v_cvt_pk_bf16_f32 v51, v51, v52
	v_cvt_pk_bf16_f32 v52, v69, v55
	v_addc_co_u32_e32 v55, vcc, 0, v157, vcc
	v_pk_fma_f32 v[40:41], v[40:41], v[68:69], v[48:49] op_sel_hi:[1,0,1]
	v_pk_fma_f32 v[38:39], v[38:39], v[68:69], v[46:47] op_sel_hi:[1,0,1]
	v_max_f32_e32 v34, 0, v34
	v_max_f32_e32 v35, 0, v35
	v_max_f32_e32 v36, 0, v36
	v_cvt_pk_bf16_f32 v53, v56, v53
	global_store_dwordx4 v[54:55], v[50:53], off nt
	v_max_f32_e32 v37, 0, v37
	v_max_f32_e32 v38, 0, v38
	v_mul_f32_e32 v50, v34, v34
	v_max_f32_e32 v34, 0, v39
	v_mul_f32_e32 v39, v35, v35
	v_max_f32_e32 v35, 0, v40
	v_mul_f32_e32 v40, v36, v36
	v_max_f32_e32 v36, 0, v41
	v_mul_f32_e32 v34, v34, v34
	v_mul_f32_e32 v35, v35, v35
	v_mul_f32_e32 v36, v36, v36
	v_mul_f32_e32 v37, v37, v37
	v_mul_f32_e32 v38, v38, v38
	v_cvt_pk_bf16_f32 v34, v38, v34
	v_cvt_pk_bf16_f32 v35, v35, v36
	v_cvt_pk_bf16_f32 v36, v50, v39
	v_cvt_pk_bf16_f32 v37, v40, v37
	global_store_dwordx4 v[66:67], v[34:37], off offset:256 nt
	global_load_dword v36, v[158:159], off offset:640
	s_mov_b64 s[2:3], 0x140000
	v_lshl_add_u64 v[34:35], v[156:157], 0, s[2:3]
	s_mov_b32 s2, 0x140000
	s_waitcnt vmcnt(0)
; #define PG8_BAR __builtin_amdgcn_s_barrier()
; DI unsigned pk2(float lo, float hi) { return pg8::cvt_pk_bf16(lo, hi); }
; template <class Epi, class Sched, bool ALIGN_EPI = false, bool SP2 = false>
; __device__ __forceinline__ void gemm_phase(PG8_LAS unsigned char* lds, const Gemm g, const Sched& S, const Epi& E) {
;     ...
;         if (!has_next) break;
; #pragma unroll
;         for (int a = 0; a < 2; ++a)
; #pragma unroll
;             for (int b = 0; b < 2; ++b)
; #pragma unroll
;                 for (int m = 0; m < 4; ++m)
; #pragma unroll
;                     for (int n = 0; n < 2; ++n) acc[a][b][m][n] = (f32x4){0.f, 0.f, 0.f, 0.f};
;         cur = nxt; cA = nA; cB = nB; ++ui;
;         if constexpr (ALIGN_EPI) { if (wr == 1) PG8_BAR; }
;     DI void operator()(const f32x4 (&acc)[2][2][4][2], const Unit& u, int wr, int wc, int fr, int fq) const {
;     ...
;         for (int ai = 0; ai < 2; ++ai)
; #pragma unroll
;             for (int m = 0; m < 4; ++m) { bf16* rowp = O + (size_t)(row0 + ai * 128 + m * 16) * 4096 + col0;
;                 const float rstd = rsqrtf(rowss[row0 + ai * 128 + m * 16] * (1.0f / 1024.0f) + 1e-6f);
; #pragma unroll
;                 for (int bj = 0; bj < 2; ++bj) { f32x4 v0 = acc[ai][bj][m][0] * rstd + bs[bj][0], v1 = acc[ai][bj][m][1] * rstd + bs[bj][1];
; #pragma unroll
;                     for (int i = 0; i < 4; ++i) { float a = fmaxf(v0[i], 0.f), b = fmaxf(v1[i], 0.f); v0[i] = a * a; v1[i] = b * b; }
;                     v4u w; w.x = pk2(v0[0], v0[1]); w.y = pk2(v0[2], v0[3]); w.z = pk2(v1[0], v1[1]); w.w = pk2(v1[2], v1[3]);
;                     *(v4u*)(rowp + bj * 128) = w; } }
	v_fmamk_f32 v36, v36, 0x3a800000, v192
	v_cmp_gt_f32_e32 vcc, s17, v36
	v_mul_f32_e32 v37, 0x4b800000, v36
	s_nop 0
	v_cndmask_b32_e32 v36, v36, v37, vcc
	v_rsq_f32_e32 v36, v36
	s_nop 0
	v_mul_f32_e32 v37, 0x45800000, v36
	v_cndmask_b32_e32 v36, v36, v37, vcc
	v_pk_fma_f32 v[26:27], v[26:27], v[36:37], v[58:59] op_sel_hi:[1,0,1]
	v_pk_fma_f32 v[30:31], v[30:31], v[36:37], v[62:63] op_sel_hi:[1,0,1]
	v_pk_fma_f32 v[28:29], v[28:29], v[36:37], v[60:61] op_sel_hi:[1,0,1]
	v_max_f32_e32 v26, 0, v26
	v_pk_fma_f32 v[32:33], v[32:33], v[36:37], v[64:65] op_sel_hi:[1,0,1]
	v_max_f32_e32 v30, 0, v30
	v_mul_f32_e32 v37, v26, v26
	v_max_f32_e32 v26, 0, v31
	v_max_f32_e32 v27, 0, v27
	v_max_f32_e32 v28, 0, v28
	v_mul_f32_e32 v30, v30, v30
	v_mul_f32_e32 v26, v26, v26
	v_mul_f32_e32 v31, v27, v27
	v_max_f32_e32 v27, 0, v32
	v_mul_f32_e32 v32, v28, v28
	v_max_f32_e32 v28, 0, v33
	v_mul_f32_e32 v27, v27, v27
	v_max_f32_e32 v29, 0, v29
	v_mul_f32_e32 v28, v28, v28
	v_cvt_pk_bf16_f32 v26, v30, v26
	v_add_co_u32_e32 v30, vcc, s2, v156
	v_pk_fma_f32 v[20:21], v[20:21], v[36:37], v[44:45] op_sel_hi:[1,0,1]
	v_pk_fma_f32 v[18:19], v[18:19], v[36:37], v[42:43] op_sel_hi:[1,0,1]
	v_mul_f32_e32 v29, v29, v29
	v_cvt_pk_bf16_f32 v27, v27, v28
	v_cvt_pk_bf16_f32 v28, v37, v31
	v_addc_co_u32_e32 v31, vcc, 0, v157, vcc
	v_pk_fma_f32 v[24:25], v[24:25], v[36:37], v[48:49] op_sel_hi:[1,0,1]
	v_pk_fma_f32 v[22:23], v[22:23], v[36:37], v[46:47] op_sel_hi:[1,0,1]
	v_max_f32_e32 v18, 0, v18
	v_max_f32_e32 v19, 0, v19
	v_max_f32_e32 v20, 0, v20
	v_cvt_pk_bf16_f32 v29, v32, v29
	global_store_dwordx4 v[30:31], v[26:29], off nt
	v_max_f32_e32 v21, 0, v21
	v_max_f32_e32 v22, 0, v22
	v_mul_f32_e32 v26, v18, v18
	v_max_f32_e32 v18, 0, v23
	v_mul_f32_e32 v23, v19, v19
	v_max_f32_e32 v19, 0, v24
	v_mul_f32_e32 v24, v20, v20
	v_max_f32_e32 v20, 0, v25
	v_mul_f32_e32 v18, v18, v18
	v_mul_f32_e32 v19, v19, v19
	v_mul_f32_e32 v20, v20, v20
	v_mul_f32_e32 v21, v21, v21
	v_mul_f32_e32 v22, v22, v22
	v_cvt_pk_bf16_f32 v18, v22, v18
	v_cvt_pk_bf16_f32 v19, v19, v20
	v_cvt_pk_bf16_f32 v20, v26, v23
	v_cvt_pk_bf16_f32 v21, v24, v21
	global_store_dwordx4 v[34:35], v[18:21], off offset:256 nt
	global_load_dword v20, v[158:159], off offset:704
	s_mov_b64 s[2:3], 0x160000
	v_lshl_add_u64 v[18:19], v[156:157], 0, s[2:3]
	s_mov_b32 s2, 0x160000
	s_waitcnt vmcnt(0)
	v_fmamk_f32 v20, v20, 0x3a800000, v192
	v_cmp_gt_f32_e32 vcc, s17, v20
	v_mul_f32_e32 v21, 0x4b800000, v20
	s_nop 0
	v_cndmask_b32_e32 v20, v20, v21, vcc
	v_rsq_f32_e32 v20, v20
	s_nop 0
	v_mul_f32_e32 v21, 0x45800000, v20
	v_cndmask_b32_e32 v20, v20, v21, vcc
	v_pk_fma_f32 v[10:11], v[10:11], v[20:21], v[58:59] op_sel_hi:[1,0,1]
	v_pk_fma_f32 v[14:15], v[14:15], v[20:21], v[62:63] op_sel_hi:[1,0,1]
	v_pk_fma_f32 v[12:13], v[12:13], v[20:21], v[60:61] op_sel_hi:[1,0,1]
	v_max_f32_e32 v10, 0, v10
	v_pk_fma_f32 v[16:17], v[16:17], v[20:21], v[64:65] op_sel_hi:[1,0,1]
	v_max_f32_e32 v14, 0, v14
	v_mul_f32_e32 v21, v10, v10
	v_max_f32_e32 v10, 0, v15
	v_max_f32_e32 v11, 0, v11
	v_max_f32_e32 v12, 0, v12
	v_mul_f32_e32 v14, v14, v14
	v_mul_f32_e32 v10, v10, v10
	v_mul_f32_e32 v15, v11, v11
	v_max_f32_e32 v11, 0, v16
	v_mul_f32_e32 v16, v12, v12
	v_max_f32_e32 v12, 0, v17
	v_mul_f32_e32 v11, v11, v11
	v_max_f32_e32 v13, 0, v13
	v_mul_f32_e32 v12, v12, v12
	v_cvt_pk_bf16_f32 v10, v14, v10
	v_add_co_u32_e32 v14, vcc, s2, v156
	v_pk_fma_f32 v[4:5], v[4:5], v[20:21], v[44:45] op_sel_hi:[1,0,1]
	v_pk_fma_f32 v[2:3], v[2:3], v[20:21], v[42:43] op_sel_hi:[1,0,1]
	v_mul_f32_e32 v13, v13, v13
	v_cvt_pk_bf16_f32 v11, v11, v12
	v_cvt_pk_bf16_f32 v12, v21, v15
	v_addc_co_u32_e32 v15, vcc, 0, v157, vcc
	v_pk_fma_f32 v[8:9], v[8:9], v[20:21], v[48:49] op_sel_hi:[1,0,1]
	v_pk_fma_f32 v[6:7], v[6:7], v[20:21], v[46:47] op_sel_hi:[1,0,1]
	v_max_f32_e32 v2, 0, v2
	v_max_f32_e32 v3, 0, v3
	v_max_f32_e32 v4, 0, v4
	v_cvt_pk_bf16_f32 v13, v16, v13
	global_store_dwordx4 v[14:15], v[10:13], off nt
	v_max_f32_e32 v5, 0, v5
	v_max_f32_e32 v6, 0, v6
	v_mul_f32_e32 v10, v2, v2
	v_max_f32_e32 v2, 0, v7
	v_mul_f32_e32 v7, v3, v3
	v_max_f32_e32 v3, 0, v8
	v_mul_f32_e32 v8, v4, v4
	v_max_f32_e32 v4, 0, v9
	v_mul_f32_e32 v2, v2, v2
	v_mul_f32_e32 v3, v3, v3
	v_mul_f32_e32 v4, v4, v4
	v_mul_f32_e32 v5, v5, v5
	s_mov_b64 s[2:3], -1
	s_andn2_b64 vcc, exec, s[4:5]
	v_mul_f32_e32 v6, v6, v6
	v_cvt_pk_bf16_f32 v2, v6, v2
	v_cvt_pk_bf16_f32 v3, v3, v4
	v_cvt_pk_bf16_f32 v4, v10, v7
	v_cvt_pk_bf16_f32 v5, v8, v5
	global_store_dwordx4 v[18:19], v[2:5], off offset:256 nt
	s_cbranch_vccnz .LBB0_731
	s_andn2_b64 vcc, exec, s[6:7]
	s_cbranch_vccnz .LBB0_730
	s_barrier
	s_branch .LBB0_730
